# x19 + dead shuffle-address code removed at the 16 permlane16 swap sites of the GIN epilogue too
# speedup vs baseline: 1.0034x; 1.0034x over previous
; __device__ __forceinline__ float dot4(const f32x4& v) { return (v[0] * v[0] + v[1] * v[1]) + (v[2] * v[2] + v[3] * v[3]); }
;     __device__ __forceinline__ void operator()(const f32x4 (&acc)[2][2][4][2], const Unit& u, int wr, int wc, int fr, int fq) const {
;     ...
;                         if (colw >= ZCQ && colw < ZKR) { float sb = dot4(v0) + dot4(v1); sb += __shfl_xor(sb, 16); sb += __shfl_xor(sb, 32);
;                             if (fq == 0) rstat[(size_t)row * 16 + ((colw - ZCQ) >> 5)] = sb; }
.LBB0_389:
	s_andn2_b64 vcc, exec, s[42:43]
	s_cbranch_vccnz .LBB0_393
	v_mul_f32_e32 v147, v127, v127
	v_mul_f32_e32 v150, v129, v129
	v_fmac_f32_e32 v147, v126, v126
	v_fmac_f32_e32 v150, v128, v128
	v_add_f32_e32 v147, v147, v150
	v_mul_f32_e32 v150, v123, v123
	v_mul_f32_e32 v151, v125, v125
	v_fmac_f32_e32 v150, v122, v122
	v_fmac_f32_e32 v151, v124, v124
	v_add_f32_e32 v150, v150, v151
	v_add_f32_e32 v147, v150, v147
	v_mov_b32_e32 v150, v147
	s_nop 1
	v_permlane16_swap_b32_e32 v150, v147
	s_waitcnt lgkmcnt(0)
	v_add_f32_e32 v147, v147, v150
	v_mov_b32_e32 v150, v147
	s_nop 1
	v_permlane32_swap_b32_e32 v150, v147
	s_and_saveexec_b64 s[42:43], s[38:39]
	s_cbranch_execz .LBB0_392
	v_lshl_add_u64 v[152:153], s[50:51], 0, v[148:149]
	s_lshr_b32 s76, s19, 3
	v_lshl_add_u64 v[152:153], v[152:153], 0, s[76:77]
	s_waitcnt lgkmcnt(0)
	v_add_f32_e32 v147, v147, v150
	global_store_dword v[152:153], v147, off

; __device__ __forceinline__ float dot4(const f32x4& v) { return (v[0] * v[0] + v[1] * v[1]) + (v[2] * v[2] + v[3] * v[3]); }
;     __device__ __forceinline__ void operator()(const f32x4 (&acc)[2][2][4][2], const Unit& u, int wr, int wc, int fr, int fq) const {
;     ...
;                         if (colw >= ZCQ && colw < ZKR) { float sb = dot4(v0) + dot4(v1); sb += __shfl_xor(sb, 16); sb += __shfl_xor(sb, 32);
;                             if (fq == 0) rstat[(size_t)row * 16 + ((colw - ZCQ) >> 5)] = sb; }
.LBB0_399:
	s_andn2_b64 vcc, exec, s[66:67]
	s_cbranch_vccnz .LBB0_403
	v_mul_f32_e32 v122, v119, v119
	v_mul_f32_e32 v123, v121, v121
	v_fmac_f32_e32 v122, v118, v118
	v_fmac_f32_e32 v123, v120, v120
	v_add_f32_e32 v122, v122, v123
	v_mul_f32_e32 v123, v115, v115
	v_mul_f32_e32 v124, v117, v117
	v_fmac_f32_e32 v123, v114, v114
	v_fmac_f32_e32 v124, v116, v116
	v_add_f32_e32 v123, v123, v124
	v_add_f32_e32 v122, v123, v122
	v_mov_b32_e32 v123, v122
	s_nop 1
	v_permlane16_swap_b32_e32 v123, v122
	s_waitcnt lgkmcnt(0)
	v_add_f32_e32 v122, v122, v123
	v_mov_b32_e32 v123, v122
	s_nop 1
	v_permlane32_swap_b32_e32 v123, v122
	s_and_saveexec_b64 s[66:67], s[38:39]
	s_cbranch_execz .LBB0_402
	v_lshl_add_u64 v[124:125], s[50:51], 0, v[148:149]
	s_lshr_b32 s76, s19, 3
	v_lshl_add_u64 v[124:125], v[124:125], 0, s[76:77]
	s_waitcnt lgkmcnt(0)
	v_add_f32_e32 v122, v122, v123
	global_store_dword v[124:125], v122, off

; __device__ __forceinline__ float dot4(const f32x4& v) { return (v[0] * v[0] + v[1] * v[1]) + (v[2] * v[2] + v[3] * v[3]); }
;     __device__ __forceinline__ void operator()(const f32x4 (&acc)[2][2][4][2], const Unit& u, int wr, int wc, int fr, int fq) const {
;     ...
;                         if (colw >= ZCQ && colw < ZKR) { float sb = dot4(v0) + dot4(v1); sb += __shfl_xor(sb, 16); sb += __shfl_xor(sb, 32);
;                             if (fq == 0) rstat[(size_t)row * 16 + ((colw - ZCQ) >> 5)] = sb; }
.LBB0_409:
	s_andn2_b64 vcc, exec, s[66:67]
	s_cbranch_vccnz .LBB0_413
	v_mul_f32_e32 v117, v111, v111
	v_mul_f32_e32 v118, v113, v113
	v_fmac_f32_e32 v117, v110, v110
	v_fmac_f32_e32 v118, v112, v112
	v_add_f32_e32 v117, v117, v118
	v_mul_f32_e32 v118, v107, v107
	v_mul_f32_e32 v119, v109, v109
	v_fmac_f32_e32 v118, v106, v106
	v_fmac_f32_e32 v119, v108, v108
	v_add_f32_e32 v118, v118, v119
	v_add_f32_e32 v117, v118, v117
	v_mov_b32_e32 v118, v117
	s_nop 1
	v_permlane16_swap_b32_e32 v118, v117
	s_waitcnt lgkmcnt(0)
	v_add_f32_e32 v117, v117, v118
	v_mov_b32_e32 v118, v117
	s_nop 1
	v_permlane32_swap_b32_e32 v118, v117
	s_and_saveexec_b64 s[66:67], s[38:39]
	s_cbranch_execz .LBB0_412
	v_lshl_add_u64 v[120:121], s[50:51], 0, v[114:115]
	s_lshr_b32 s76, s19, 3
	v_lshl_add_u64 v[120:121], v[120:121], 0, s[76:77]
	s_waitcnt lgkmcnt(0)
	v_add_f32_e32 v117, v117, v118
	global_store_dword v[120:121], v117, off

; __device__ __forceinline__ float dot4(const f32x4& v) { return (v[0] * v[0] + v[1] * v[1]) + (v[2] * v[2] + v[3] * v[3]); }
;     __device__ __forceinline__ void operator()(const f32x4 (&acc)[2][2][4][2], const Unit& u, int wr, int wc, int fr, int fq) const {
;     ...
;                         if (colw >= ZCQ && colw < ZKR) { float sb = dot4(v0) + dot4(v1); sb += __shfl_xor(sb, 16); sb += __shfl_xor(sb, 32);
;                             if (fq == 0) rstat[(size_t)row * 16 + ((colw - ZCQ) >> 5)] = sb; }
.LBB0_419:
	s_andn2_b64 vcc, exec, s[66:67]
	s_cbranch_vccnz .LBB0_423
	v_mul_f32_e32 v106, v103, v103
	v_mul_f32_e32 v107, v105, v105
	v_fmac_f32_e32 v106, v102, v102
	v_fmac_f32_e32 v107, v104, v104
	v_add_f32_e32 v106, v106, v107
	v_mul_f32_e32 v107, v99, v99
	v_mul_f32_e32 v108, v101, v101
	v_fmac_f32_e32 v107, v98, v98
	v_fmac_f32_e32 v108, v100, v100
	v_add_f32_e32 v107, v107, v108
	v_add_f32_e32 v106, v107, v106
	v_mov_b32_e32 v107, v106
	s_nop 1
	v_permlane16_swap_b32_e32 v107, v106
	s_waitcnt lgkmcnt(0)
	v_add_f32_e32 v106, v106, v107
	v_mov_b32_e32 v107, v106
	s_nop 1
	v_permlane32_swap_b32_e32 v107, v106
	s_and_saveexec_b64 s[66:67], s[38:39]
	s_cbranch_execz .LBB0_422
	v_lshl_add_u64 v[108:109], s[50:51], 0, v[114:115]
	s_lshr_b32 s76, s19, 3
	v_lshl_add_u64 v[108:109], v[108:109], 0, s[76:77]
	s_waitcnt lgkmcnt(0)
	v_add_f32_e32 v106, v106, v107
	global_store_dword v[108:109], v106, off

; __device__ __forceinline__ float dot4(const f32x4& v) { return (v[0] * v[0] + v[1] * v[1]) + (v[2] * v[2] + v[3] * v[3]); }
;     __device__ __forceinline__ void operator()(const f32x4 (&acc)[2][2][4][2], const Unit& u, int wr, int wc, int fr, int fq) const {
;     ...
;                         if (colw >= ZCQ && colw < ZKR) { float sb = dot4(v0) + dot4(v1); sb += __shfl_xor(sb, 16); sb += __shfl_xor(sb, 32);
;                             if (fq == 0) rstat[(size_t)row * 16 + ((colw - ZCQ) >> 5)] = sb; }
.LBB0_429:
	s_andn2_b64 vcc, exec, s[66:67]
	s_cbranch_vccnz .LBB0_433
	v_mul_f32_e32 v101, v93, v93
	v_mul_f32_e32 v102, v95, v95
	v_fmac_f32_e32 v101, v92, v92
	v_fmac_f32_e32 v102, v94, v94
	v_add_f32_e32 v101, v101, v102
	v_mul_f32_e32 v102, v89, v89
	v_mul_f32_e32 v103, v91, v91
	v_fmac_f32_e32 v102, v88, v88
	v_fmac_f32_e32 v103, v90, v90
	v_add_f32_e32 v102, v102, v103
	v_add_f32_e32 v101, v102, v101
	v_mov_b32_e32 v102, v101
	s_nop 1
	v_permlane16_swap_b32_e32 v102, v101
	s_waitcnt lgkmcnt(0)
	v_add_f32_e32 v101, v101, v102
	v_mov_b32_e32 v102, v101
	s_nop 1
	v_permlane32_swap_b32_e32 v102, v101
	s_and_saveexec_b64 s[66:67], s[38:39]
	s_cbranch_execz .LBB0_432
	v_lshl_add_u64 v[104:105], s[50:51], 0, v[98:99]
	s_lshr_b32 s76, s19, 3
	v_lshl_add_u64 v[104:105], v[104:105], 0, s[76:77]
	s_waitcnt lgkmcnt(0)
	v_add_f32_e32 v101, v101, v102
	global_store_dword v[104:105], v101, off

; __device__ __forceinline__ float dot4(const f32x4& v) { return (v[0] * v[0] + v[1] * v[1]) + (v[2] * v[2] + v[3] * v[3]); }
;     __device__ __forceinline__ void operator()(const f32x4 (&acc)[2][2][4][2], const Unit& u, int wr, int wc, int fr, int fq) const {
;     ...
;                         if (colw >= ZCQ && colw < ZKR) { float sb = dot4(v0) + dot4(v1); sb += __shfl_xor(sb, 16); sb += __shfl_xor(sb, 32);
;                             if (fq == 0) rstat[(size_t)row * 16 + ((colw - ZCQ) >> 5)] = sb; }
.LBB0_439:
	s_andn2_b64 vcc, exec, s[66:67]
	s_cbranch_vccnz .LBB0_443
	v_mul_f32_e32 v88, v85, v85
	v_mul_f32_e32 v89, v87, v87
	v_fmac_f32_e32 v88, v84, v84
	v_fmac_f32_e32 v89, v86, v86
	v_add_f32_e32 v88, v88, v89
	v_mul_f32_e32 v89, v81, v81
	v_mul_f32_e32 v90, v83, v83
	v_fmac_f32_e32 v89, v80, v80
	v_fmac_f32_e32 v90, v82, v82
	v_add_f32_e32 v89, v89, v90
	v_add_f32_e32 v88, v89, v88
	v_mov_b32_e32 v89, v88
	s_nop 1
	v_permlane16_swap_b32_e32 v89, v88
	s_waitcnt lgkmcnt(0)
	v_add_f32_e32 v88, v88, v89
	v_mov_b32_e32 v89, v88
	s_nop 1
	v_permlane32_swap_b32_e32 v89, v88
	s_and_saveexec_b64 s[66:67], s[38:39]
	s_cbranch_execz .LBB0_442
	v_lshl_add_u64 v[90:91], s[50:51], 0, v[98:99]
	s_lshr_b32 s76, s19, 3
	v_lshl_add_u64 v[90:91], v[90:91], 0, s[76:77]
	s_waitcnt lgkmcnt(0)
	v_add_f32_e32 v88, v88, v89
	global_store_dword v[90:91], v88, off

; __device__ __forceinline__ float dot4(const f32x4& v) { return (v[0] * v[0] + v[1] * v[1]) + (v[2] * v[2] + v[3] * v[3]); }
;     __device__ __forceinline__ void operator()(const f32x4 (&acc)[2][2][4][2], const Unit& u, int wr, int wc, int fr, int fq) const {
;     ...
;                         if (colw >= ZCQ && colw < ZKR) { float sb = dot4(v0) + dot4(v1); sb += __shfl_xor(sb, 16); sb += __shfl_xor(sb, 32);
;                             if (fq == 0) rstat[(size_t)row * 16 + ((colw - ZCQ) >> 5)] = sb; }
.LBB0_449:
	s_andn2_b64 vcc, exec, s[66:67]
	s_cbranch_vccnz .LBB0_453
	v_mul_f32_e32 v83, v77, v77
	v_mul_f32_e32 v84, v79, v79
	v_fmac_f32_e32 v83, v76, v76
	v_fmac_f32_e32 v84, v78, v78
	v_add_f32_e32 v83, v83, v84
	v_mul_f32_e32 v84, v73, v73
	v_mul_f32_e32 v85, v75, v75
	v_fmac_f32_e32 v84, v72, v72
	v_fmac_f32_e32 v85, v74, v74
	v_add_f32_e32 v84, v84, v85
	v_add_f32_e32 v83, v84, v83
	v_mov_b32_e32 v84, v83
	s_nop 1
	v_permlane16_swap_b32_e32 v84, v83
	s_waitcnt lgkmcnt(0)
	v_add_f32_e32 v83, v83, v84
	v_mov_b32_e32 v84, v83
	s_nop 1
	v_permlane32_swap_b32_e32 v84, v83
	s_and_saveexec_b64 s[66:67], s[38:39]
	s_cbranch_execz .LBB0_452
	v_lshl_add_u64 v[86:87], s[50:51], 0, v[80:81]
	s_lshr_b32 s76, s19, 3
	v_lshl_add_u64 v[86:87], v[86:87], 0, s[76:77]
	s_waitcnt lgkmcnt(0)
	v_add_f32_e32 v83, v83, v84
	global_store_dword v[86:87], v83, off

; __device__ __forceinline__ float dot4(const f32x4& v) { return (v[0] * v[0] + v[1] * v[1]) + (v[2] * v[2] + v[3] * v[3]); }
;     __device__ __forceinline__ void operator()(const f32x4 (&acc)[2][2][4][2], const Unit& u, int wr, int wc, int fr, int fq) const {
;     ...
;                         if (colw >= ZCQ && colw < ZKR) { float sb = dot4(v0) + dot4(v1); sb += __shfl_xor(sb, 16); sb += __shfl_xor(sb, 32);
;                             if (fq == 0) rstat[(size_t)row * 16 + ((colw - ZCQ) >> 5)] = sb; }
.LBB0_459:
	s_andn2_b64 vcc, exec, s[66:67]
	s_cbranch_vccnz .LBB0_463
	v_mul_f32_e32 v72, v69, v69
	v_mul_f32_e32 v73, v71, v71
	v_fmac_f32_e32 v72, v68, v68
	v_fmac_f32_e32 v73, v70, v70
	v_add_f32_e32 v72, v72, v73
	v_mul_f32_e32 v73, v65, v65
	v_mul_f32_e32 v74, v67, v67
	v_fmac_f32_e32 v73, v64, v64
	v_fmac_f32_e32 v74, v66, v66
	v_add_f32_e32 v73, v73, v74
	v_add_f32_e32 v72, v73, v72
	v_mov_b32_e32 v73, v72
	s_nop 1
	v_permlane16_swap_b32_e32 v73, v72
	s_waitcnt lgkmcnt(0)
	v_add_f32_e32 v72, v72, v73
	v_mov_b32_e32 v73, v72
	s_nop 1
	v_permlane32_swap_b32_e32 v73, v72
	s_and_saveexec_b64 s[66:67], s[38:39]
	s_cbranch_execz .LBB0_462
	v_lshl_add_u64 v[74:75], s[50:51], 0, v[80:81]
	s_lshr_b32 s76, s18, 3
	v_lshl_add_u64 v[74:75], v[74:75], 0, s[76:77]
	s_waitcnt lgkmcnt(0)
	v_add_f32_e32 v72, v72, v73
	global_store_dword v[74:75], v72, off

; __device__ __forceinline__ float dot4(const f32x4& v) { return (v[0] * v[0] + v[1] * v[1]) + (v[2] * v[2] + v[3] * v[3]); }
;     __device__ __forceinline__ void operator()(const f32x4 (&acc)[2][2][4][2], const Unit& u, int wr, int wc, int fr, int fq) const {
;     ...
;                         if (colw >= ZCQ && colw < ZKR) { float sb = dot4(v0) + dot4(v1); sb += __shfl_xor(sb, 16); sb += __shfl_xor(sb, 32);
;                             if (fq == 0) rstat[(size_t)row * 16 + ((colw - ZCQ) >> 5)] = sb; }
.LBB0_469:
	s_andn2_b64 vcc, exec, s[66:67]
	s_cbranch_vccnz .LBB0_473
	v_mul_f32_e32 v67, v61, v61
	v_mul_f32_e32 v68, v63, v63
	v_fmac_f32_e32 v67, v60, v60
	v_fmac_f32_e32 v68, v62, v62
	v_add_f32_e32 v67, v67, v68
	v_mul_f32_e32 v68, v57, v57
	v_mul_f32_e32 v69, v59, v59
	v_fmac_f32_e32 v68, v56, v56
	v_fmac_f32_e32 v69, v58, v58
	v_add_f32_e32 v68, v68, v69
	v_add_f32_e32 v67, v68, v67
	v_mov_b32_e32 v68, v67
	s_nop 1
	v_permlane16_swap_b32_e32 v68, v67
	s_waitcnt lgkmcnt(0)
	v_add_f32_e32 v67, v67, v68
	v_mov_b32_e32 v68, v67
	s_nop 1
	v_permlane32_swap_b32_e32 v68, v67
	s_and_saveexec_b64 s[66:67], s[38:39]
	s_cbranch_execz .LBB0_472
	v_lshl_add_u64 v[70:71], s[50:51], 0, v[64:65]
	s_lshr_b32 s76, s18, 3
	v_lshl_add_u64 v[70:71], v[70:71], 0, s[76:77]
	s_waitcnt lgkmcnt(0)
	v_add_f32_e32 v67, v67, v68
	global_store_dword v[70:71], v67, off

; __device__ __forceinline__ float dot4(const f32x4& v) { return (v[0] * v[0] + v[1] * v[1]) + (v[2] * v[2] + v[3] * v[3]); }
;     __device__ __forceinline__ void operator()(const f32x4 (&acc)[2][2][4][2], const Unit& u, int wr, int wc, int fr, int fq) const {
;     ...
;                         if (colw >= ZCQ && colw < ZKR) { float sb = dot4(v0) + dot4(v1); sb += __shfl_xor(sb, 16); sb += __shfl_xor(sb, 32);
;                             if (fq == 0) rstat[(size_t)row * 16 + ((colw - ZCQ) >> 5)] = sb; }
.LBB0_479:
	s_andn2_b64 vcc, exec, s[66:67]
	s_cbranch_vccnz .LBB0_483
	v_mul_f32_e32 v56, v53, v53
	v_mul_f32_e32 v57, v55, v55
	v_fmac_f32_e32 v56, v52, v52
	v_fmac_f32_e32 v57, v54, v54
	v_add_f32_e32 v56, v56, v57
	v_mul_f32_e32 v57, v49, v49
	v_mul_f32_e32 v58, v51, v51
	v_fmac_f32_e32 v57, v48, v48
	v_fmac_f32_e32 v58, v50, v50
	v_add_f32_e32 v57, v57, v58
	v_add_f32_e32 v56, v57, v56
	v_mov_b32_e32 v57, v56
	s_nop 1
	v_permlane16_swap_b32_e32 v57, v56
	s_waitcnt lgkmcnt(0)
	v_add_f32_e32 v56, v56, v57
	v_mov_b32_e32 v57, v56
	s_nop 1
	v_permlane32_swap_b32_e32 v57, v56
	s_and_saveexec_b64 s[66:67], s[38:39]
	s_cbranch_execz .LBB0_482
	v_lshl_add_u64 v[58:59], s[50:51], 0, v[64:65]
	s_lshr_b32 s76, s18, 3
	v_lshl_add_u64 v[58:59], v[58:59], 0, s[76:77]
	s_waitcnt lgkmcnt(0)
	v_add_f32_e32 v56, v56, v57
	global_store_dword v[58:59], v56, off

; __device__ __forceinline__ float dot4(const f32x4& v) { return (v[0] * v[0] + v[1] * v[1]) + (v[2] * v[2] + v[3] * v[3]); }
;     __device__ __forceinline__ void operator()(const f32x4 (&acc)[2][2][4][2], const Unit& u, int wr, int wc, int fr, int fq) const {
;     ...
;                         if (colw >= ZCQ && colw < ZKR) { float sb = dot4(v0) + dot4(v1); sb += __shfl_xor(sb, 16); sb += __shfl_xor(sb, 32);
;                             if (fq == 0) rstat[(size_t)row * 16 + ((colw - ZCQ) >> 5)] = sb; }
.LBB0_489:
	s_andn2_b64 vcc, exec, s[66:67]
	s_cbranch_vccnz .LBB0_493
	v_mul_f32_e32 v51, v45, v45
	v_mul_f32_e32 v52, v47, v47
	v_fmac_f32_e32 v51, v44, v44
	v_fmac_f32_e32 v52, v46, v46
	v_add_f32_e32 v51, v51, v52
	v_mul_f32_e32 v52, v41, v41
	v_mul_f32_e32 v53, v43, v43
	v_fmac_f32_e32 v52, v40, v40
	v_fmac_f32_e32 v53, v42, v42
	v_add_f32_e32 v52, v52, v53
	v_add_f32_e32 v51, v52, v51
	v_mov_b32_e32 v52, v51
	s_nop 1
	v_permlane16_swap_b32_e32 v52, v51
	s_waitcnt lgkmcnt(0)
	v_add_f32_e32 v51, v51, v52
	v_mov_b32_e32 v52, v51
	s_nop 1
	v_permlane32_swap_b32_e32 v52, v51
	s_and_saveexec_b64 s[66:67], s[38:39]
	s_cbranch_execz .LBB0_492
	v_lshl_add_u64 v[54:55], s[50:51], 0, v[48:49]
	s_lshr_b32 s76, s18, 3
	v_lshl_add_u64 v[54:55], v[54:55], 0, s[76:77]
	s_waitcnt lgkmcnt(0)
	v_add_f32_e32 v51, v51, v52
	global_store_dword v[54:55], v51, off

; __device__ __forceinline__ float dot4(const f32x4& v) { return (v[0] * v[0] + v[1] * v[1]) + (v[2] * v[2] + v[3] * v[3]); }
;     __device__ __forceinline__ void operator()(const f32x4 (&acc)[2][2][4][2], const Unit& u, int wr, int wc, int fr, int fq) const {
;     ...
;                         if (colw >= ZCQ && colw < ZKR) { float sb = dot4(v0) + dot4(v1); sb += __shfl_xor(sb, 16); sb += __shfl_xor(sb, 32);
;                             if (fq == 0) rstat[(size_t)row * 16 + ((colw - ZCQ) >> 5)] = sb; }
.LBB0_499:
	s_andn2_b64 vcc, exec, s[66:67]
	s_cbranch_vccnz .LBB0_503
	v_mul_f32_e32 v40, v37, v37
	v_mul_f32_e32 v41, v39, v39
	v_fmac_f32_e32 v40, v36, v36
	v_fmac_f32_e32 v41, v38, v38
	v_add_f32_e32 v40, v40, v41
	v_mul_f32_e32 v41, v33, v33
	v_mul_f32_e32 v42, v35, v35
	v_fmac_f32_e32 v41, v32, v32
	v_fmac_f32_e32 v42, v34, v34
	v_add_f32_e32 v41, v41, v42
	v_add_f32_e32 v40, v41, v40
	v_mov_b32_e32 v41, v40
	s_nop 1
	v_permlane16_swap_b32_e32 v41, v40
	s_waitcnt lgkmcnt(0)
	v_add_f32_e32 v40, v40, v41
	v_mov_b32_e32 v41, v40
	s_nop 1
	v_permlane32_swap_b32_e32 v41, v40
	s_and_saveexec_b64 s[66:67], s[38:39]
	s_cbranch_execz .LBB0_502
	v_lshl_add_u64 v[42:43], s[50:51], 0, v[48:49]
	s_lshr_b32 s76, s18, 3
	v_lshl_add_u64 v[42:43], v[42:43], 0, s[76:77]
	s_waitcnt lgkmcnt(0)
	v_add_f32_e32 v40, v40, v41
	global_store_dword v[42:43], v40, off

; __device__ __forceinline__ float dot4(const f32x4& v) { return (v[0] * v[0] + v[1] * v[1]) + (v[2] * v[2] + v[3] * v[3]); }
;     __device__ __forceinline__ void operator()(const f32x4 (&acc)[2][2][4][2], const Unit& u, int wr, int wc, int fr, int fq) const {
;     ...
;                         if (colw >= ZCQ && colw < ZKR) { float sb = dot4(v0) + dot4(v1); sb += __shfl_xor(sb, 16); sb += __shfl_xor(sb, 32);
;                             if (fq == 0) rstat[(size_t)row * 16 + ((colw - ZCQ) >> 5)] = sb; }
.LBB0_509:
	s_andn2_b64 vcc, exec, s[66:67]
	s_cbranch_vccnz .LBB0_513
	v_mul_f32_e32 v35, v29, v29
	v_mul_f32_e32 v36, v31, v31
	v_fmac_f32_e32 v35, v28, v28
	v_fmac_f32_e32 v36, v30, v30
	v_add_f32_e32 v35, v35, v36
	v_mul_f32_e32 v36, v25, v25
	v_mul_f32_e32 v37, v27, v27
	v_fmac_f32_e32 v36, v24, v24
	v_fmac_f32_e32 v37, v26, v26
	v_add_f32_e32 v36, v36, v37
	v_add_f32_e32 v35, v36, v35
	v_mov_b32_e32 v36, v35
	s_nop 1
	v_permlane16_swap_b32_e32 v36, v35
	s_waitcnt lgkmcnt(0)
	v_add_f32_e32 v35, v35, v36
	v_mov_b32_e32 v36, v35
	s_nop 1
	v_permlane32_swap_b32_e32 v36, v35
	s_and_saveexec_b64 s[66:67], s[38:39]
	s_cbranch_execz .LBB0_512
	v_lshl_add_u64 v[38:39], s[50:51], 0, v[32:33]
	s_lshr_b32 s76, s18, 3
	v_lshl_add_u64 v[38:39], v[38:39], 0, s[76:77]
	s_waitcnt lgkmcnt(0)
	v_add_f32_e32 v35, v35, v36
	global_store_dword v[38:39], v35, off

; __device__ __forceinline__ float dot4(const f32x4& v) { return (v[0] * v[0] + v[1] * v[1]) + (v[2] * v[2] + v[3] * v[3]); }
;     __device__ __forceinline__ void operator()(const f32x4 (&acc)[2][2][4][2], const Unit& u, int wr, int wc, int fr, int fq) const {
;     ...
;                         if (colw >= ZCQ && colw < ZKR) { float sb = dot4(v0) + dot4(v1); sb += __shfl_xor(sb, 16); sb += __shfl_xor(sb, 32);
;                             if (fq == 0) rstat[(size_t)row * 16 + ((colw - ZCQ) >> 5)] = sb; }
.LBB0_519:
	s_andn2_b64 vcc, exec, s[66:67]
	s_cbranch_vccnz .LBB0_523
	v_mul_f32_e32 v24, v21, v21
	v_mul_f32_e32 v25, v23, v23
	v_fmac_f32_e32 v24, v20, v20
	v_fmac_f32_e32 v25, v22, v22
	v_add_f32_e32 v24, v24, v25
	v_mul_f32_e32 v25, v17, v17
	v_mul_f32_e32 v26, v19, v19
	v_fmac_f32_e32 v25, v16, v16
	v_fmac_f32_e32 v26, v18, v18
	v_add_f32_e32 v25, v25, v26
	v_add_f32_e32 v24, v25, v24
	v_mov_b32_e32 v25, v24
	s_nop 1
	v_permlane16_swap_b32_e32 v25, v24
	s_waitcnt lgkmcnt(0)
	v_add_f32_e32 v24, v24, v25
	v_mov_b32_e32 v25, v24
	s_nop 1
	v_permlane32_swap_b32_e32 v25, v24
	s_and_saveexec_b64 s[66:67], s[38:39]
	s_cbranch_execz .LBB0_522
	v_lshl_add_u64 v[26:27], s[50:51], 0, v[32:33]
	s_lshr_b32 s76, s18, 3
	v_lshl_add_u64 v[26:27], v[26:27], 0, s[76:77]
	s_waitcnt lgkmcnt(0)
	v_add_f32_e32 v24, v24, v25
	global_store_dword v[26:27], v24, off

; __device__ __forceinline__ float dot4(const f32x4& v) { return (v[0] * v[0] + v[1] * v[1]) + (v[2] * v[2] + v[3] * v[3]); }
;     __device__ __forceinline__ void operator()(const f32x4 (&acc)[2][2][4][2], const Unit& u, int wr, int wc, int fr, int fq) const {
;     ...
;                         if (colw >= ZCQ && colw < ZKR) { float sb = dot4(v0) + dot4(v1); sb += __shfl_xor(sb, 16); sb += __shfl_xor(sb, 32);
;                             if (fq == 0) rstat[(size_t)row * 16 + ((colw - ZCQ) >> 5)] = sb; }
.LBB0_529:
	s_andn2_b64 vcc, exec, s[66:67]
	s_cbranch_vccnz .LBB0_533
	v_mul_f32_e32 v19, v13, v13
	v_mul_f32_e32 v20, v15, v15
	v_fmac_f32_e32 v19, v12, v12
	v_fmac_f32_e32 v20, v14, v14
	v_add_f32_e32 v19, v19, v20
	v_mul_f32_e32 v20, v9, v9
	v_mul_f32_e32 v21, v11, v11
	v_fmac_f32_e32 v20, v8, v8
	v_fmac_f32_e32 v21, v10, v10
	v_add_f32_e32 v20, v20, v21
	v_add_f32_e32 v19, v20, v19
	v_mov_b32_e32 v20, v19
	s_nop 1
	v_permlane16_swap_b32_e32 v20, v19
	s_waitcnt lgkmcnt(0)
	v_add_f32_e32 v19, v19, v20
	v_mov_b32_e32 v20, v19
	s_nop 1
	v_permlane32_swap_b32_e32 v20, v19
	s_and_saveexec_b64 s[66:67], s[38:39]
	s_cbranch_execz .LBB0_532
	v_lshl_add_u64 v[22:23], s[50:51], 0, v[16:17]
	s_lshr_b32 s76, s18, 3
	v_lshl_add_u64 v[22:23], v[22:23], 0, s[76:77]
	s_waitcnt lgkmcnt(0)
	v_add_f32_e32 v19, v19, v20
	global_store_dword v[22:23], v19, off

; __device__ __forceinline__ float dot4(const f32x4& v) { return (v[0] * v[0] + v[1] * v[1]) + (v[2] * v[2] + v[3] * v[3]); }
;     __device__ __forceinline__ void operator()(const f32x4 (&acc)[2][2][4][2], const Unit& u, int wr, int wc, int fr, int fq) const {
;     ...
;                         if (colw >= ZCQ && colw < ZKR) { float sb = dot4(v0) + dot4(v1); sb += __shfl_xor(sb, 16); sb += __shfl_xor(sb, 32);
;                             if (fq == 0) rstat[(size_t)row * 16 + ((colw - ZCQ) >> 5)] = sb; }
.LBB0_539:
	s_andn2_b64 vcc, exec, s[42:43]
	s_cbranch_vccnz .LBB0_543
	v_mul_f32_e32 v8, v5, v5
	v_mul_f32_e32 v9, v7, v7
	v_fmac_f32_e32 v8, v4, v4
	v_fmac_f32_e32 v9, v6, v6
	v_add_f32_e32 v8, v8, v9
	v_mul_f32_e32 v9, v1, v1
	v_mul_f32_e32 v10, v3, v3
	v_fmac_f32_e32 v9, v0, v0
	v_fmac_f32_e32 v10, v2, v2
	v_add_f32_e32 v9, v9, v10
	v_add_f32_e32 v8, v9, v8
	v_mov_b32_e32 v9, v8
	s_nop 1
	v_permlane16_swap_b32_e32 v9, v8
	s_waitcnt lgkmcnt(0)
	v_add_f32_e32 v8, v8, v9
	v_mov_b32_e32 v9, v8
	s_nop 1
	v_permlane32_swap_b32_e32 v9, v8
	s_and_saveexec_b64 s[42:43], s[38:39]
	s_cbranch_execz .LBB0_542
	v_lshl_add_u64 v[10:11], s[50:51], 0, v[16:17]
	s_lshr_b32 s76, s18, 3
	v_lshl_add_u64 v[10:11], v[10:11], 0, s[76:77]
	s_waitcnt lgkmcnt(0)
	v_add_f32_e32 v8, v8, v9
	global_store_dword v[10:11], v8, off
